# v014 + peeled first K-iteration in all five GEMM loops + SGPR-base LDS-DMA in FFN-down + fragment reads ahead of pointer math in FFN-up
# speedup vs baseline: 1.0097x; 1.0056x over previous
.Lsp_LBB0269:
	v_add_u32_e32 v143, 0x10000, v140
	ds_read_b128 v[136:139], v143
	ds_read_b128 v[144:147], v143 offset:1024
	ds_read_b128 v[148:151], v143 offset:2048
	ds_read_b128 v[152:155], v143 offset:3072
	v_add_u32_e32 v143, 0x14000, v140
	ds_read_b128 v[168:171], v143
	ds_read_b128 v[172:175], v143 offset:1024
	ds_read_b128 v[176:179], v143 offset:2048
	ds_read_b128 v[180:183], v143 offset:3072
	ds_read_b128 v[184:187], v142
	ds_read_b128 v[188:191], v142 offset:1024
	ds_read_b128 v[192:195], v142 offset:2048
	ds_read_b128 v[196:199], v142 offset:3072
	ds_read_b128 v[200:203], v142 offset:4096
	ds_read_b128 v[204:207], v142 offset:5120
	ds_read_b128 v[216:219], v142 offset:6144
	ds_read_b128 v[220:223], v142 offset:7168
	s_or_b32 s54, s35, 1
	s_lshl_b64 s[16:17], s[54:55], 7
	s_add_i32 s54, s35, 2
	s_lshl_b64 s[44:45], s[54:55], 7
	s_add_u32 s46, s66, s44
	s_addc_u32 s47, s67, s45
	s_and_b64 vcc, s[14:15], exec
	s_cselect_b32 vcc_hi, s29, s47
	s_cselect_b32 vcc_lo, s65, s46
	s_add_u32 s44, s70, s44
	s_addc_u32 s45, s71, s45
	s_and_b64 s[14:15], s[14:15], exec
	s_cselect_b32 s15, s51, s45
	s_cselect_b32 s14, s30, s44
	s_add_i32 s44, 0, 0x10000
	s_add_i32 s45, 0, 0x14000
	s_add_i32 m0, s73, 0xc000
	s_add_u32 s16, s31, s16
	s_addc_u32 s17, s34, s17
	global_load_lds_dwordx4 v130, s[16:17]
	s_add_i32 m0, s73, 0xe000
	s_nop 0
	global_load_lds_dwordx4 v132, s[16:17]
	s_waitcnt vmcnt(8)
	s_waitcnt lgkmcnt(0)
	s_barrier
	s_waitcnt lgkmcnt(0)
	v_mfma_f32_16x16x32_bf16 v[122:125], v[136:139], v[184:187], v[122:125]
	v_mfma_f32_16x16x32_bf16 v[122:125], v[144:147], v[188:191], v[122:125]
	v_mfma_f32_16x16x32_bf16 v[114:117], v[148:151], v[184:187], v[114:117]
	v_mfma_f32_16x16x32_bf16 v[114:117], v[152:155], v[188:191], v[114:117]
	v_mfma_f32_16x16x32_bf16 v[106:109], v[136:139], v[192:195], v[106:109]
	v_mfma_f32_16x16x32_bf16 v[106:109], v[144:147], v[196:199], v[106:109]
	v_mfma_f32_16x16x32_bf16 v[102:105], v[148:151], v[192:195], v[102:105]
	v_mfma_f32_16x16x32_bf16 v[102:105], v[152:155], v[196:199], v[102:105]
	v_mfma_f32_16x16x32_bf16 v[90:93], v[136:139], v[200:203], v[90:93]
	v_mfma_f32_16x16x32_bf16 v[90:93], v[144:147], v[204:207], v[90:93]
	v_mfma_f32_16x16x32_bf16 v[86:89], v[148:151], v[200:203], v[86:89]
	v_mfma_f32_16x16x32_bf16 v[86:89], v[152:155], v[204:207], v[86:89]
	v_mfma_f32_16x16x32_bf16 v[74:77], v[136:139], v[216:219], v[74:77]
	v_mfma_f32_16x16x32_bf16 v[74:77], v[144:147], v[220:223], v[74:77]
	v_mfma_f32_16x16x32_bf16 v[70:73], v[148:151], v[216:219], v[70:73]
	v_mfma_f32_16x16x32_bf16 v[70:73], v[152:155], v[220:223], v[70:73]
	v_mfma_f32_16x16x32_bf16 v[126:129], v[168:171], v[184:187], v[126:129]
	v_mfma_f32_16x16x32_bf16 v[126:129], v[172:175], v[188:191], v[126:129]
	v_mfma_f32_16x16x32_bf16 v[118:121], v[176:179], v[184:187], v[118:121]
	v_mfma_f32_16x16x32_bf16 v[118:121], v[180:183], v[188:191], v[118:121]
	v_mfma_f32_16x16x32_bf16 v[110:113], v[168:171], v[192:195], v[110:113]
	v_mfma_f32_16x16x32_bf16 v[110:113], v[172:175], v[196:199], v[110:113]
	v_mfma_f32_16x16x32_bf16 v[98:101], v[176:179], v[192:195], v[98:101]
	v_mfma_f32_16x16x32_bf16 v[98:101], v[180:183], v[196:199], v[98:101]
	v_mfma_f32_16x16x32_bf16 v[94:97], v[168:171], v[200:203], v[94:97]
	v_mfma_f32_16x16x32_bf16 v[94:97], v[172:175], v[204:207], v[94:97]
	v_mfma_f32_16x16x32_bf16 v[82:85], v[176:179], v[200:203], v[82:85]
	v_mfma_f32_16x16x32_bf16 v[82:85], v[180:183], v[204:207], v[82:85]
	v_mfma_f32_16x16x32_bf16 v[78:81], v[168:171], v[216:219], v[78:81]
	v_mfma_f32_16x16x32_bf16 v[78:81], v[172:175], v[220:223], v[78:81]
	v_mfma_f32_16x16x32_bf16 v[66:69], v[176:179], v[216:219], v[66:69]
	v_mfma_f32_16x16x32_bf16 v[66:69], v[180:183], v[220:223], v[66:69]
	s_barrier
	s_add_i32 s16, s44, s61
	s_mov_b32 m0, s16
	ds_read_b128 v[184:187], v142 offset:16384
	ds_read_b128 v[188:191], v142 offset:17408
	ds_read_b128 v[192:195], v142 offset:18432
	ds_read_b128 v[196:199], v142 offset:19456
	ds_read_b128 v[200:203], v142 offset:20480
	ds_read_b128 v[204:207], v142 offset:21504
	ds_read_b128 v[216:219], v142 offset:22528
	ds_read_b128 v[220:223], v142 offset:23552
	global_load_lds_dwordx4 v158, s[14:15]
	s_add_i32 m0, s16, 0x2000
	s_nop 0
	global_load_lds_dwordx4 v134, s[14:15]
	s_add_u32 s16, s14, 0x80000
	s_addc_u32 s17, s15, 0
	s_add_i32 s44, s45, s61
	s_mov_b32 m0, s44
	s_nop 0
	global_load_lds_dwordx4 v158, s[16:17]
	s_add_i32 m0, s44, 0x2000
	s_nop 0
	global_load_lds_dwordx4 v134, s[16:17]
	s_mov_b32 m0, s73
	s_nop 0
	global_load_lds_dwordx4 v130, vcc
	s_mov_b32 m0, s75
	s_nop 0
	global_load_lds_dwordx4 v132, vcc
	s_waitcnt vmcnt(8)
	s_waitcnt lgkmcnt(0)
	s_barrier
	s_waitcnt lgkmcnt(0)
	v_mfma_f32_16x16x32_bf16 v[58:61], v[136:139], v[184:187], v[58:61]
	v_mfma_f32_16x16x32_bf16 v[58:61], v[144:147], v[188:191], v[58:61]
	v_mfma_f32_16x16x32_bf16 v[54:57], v[148:151], v[184:187], v[54:57]
	v_mfma_f32_16x16x32_bf16 v[54:57], v[152:155], v[188:191], v[54:57]
	v_mfma_f32_16x16x32_bf16 v[42:45], v[136:139], v[192:195], v[42:45]
	v_mfma_f32_16x16x32_bf16 v[42:45], v[144:147], v[196:199], v[42:45]
	v_mfma_f32_16x16x32_bf16 v[38:41], v[148:151], v[192:195], v[38:41]
	v_mfma_f32_16x16x32_bf16 v[38:41], v[152:155], v[196:199], v[38:41]
	v_mfma_f32_16x16x32_bf16 v[26:29], v[136:139], v[200:203], v[26:29]
	v_mfma_f32_16x16x32_bf16 v[26:29], v[144:147], v[204:207], v[26:29]
	v_mfma_f32_16x16x32_bf16 v[22:25], v[148:151], v[200:203], v[22:25]
	v_mfma_f32_16x16x32_bf16 v[22:25], v[152:155], v[204:207], v[22:25]
	v_mfma_f32_16x16x32_bf16 v[10:13], v[136:139], v[216:219], v[10:13]
	v_mfma_f32_16x16x32_bf16 v[10:13], v[144:147], v[220:223], v[10:13]
	v_mfma_f32_16x16x32_bf16 v[2:5], v[148:151], v[216:219], v[2:5]
	v_mfma_f32_16x16x32_bf16 v[2:5], v[152:155], v[220:223], v[2:5]
	v_mfma_f32_16x16x32_bf16 v[62:65], v[168:171], v[184:187], v[62:65]
	v_mfma_f32_16x16x32_bf16 v[62:65], v[172:175], v[188:191], v[62:65]
	v_mfma_f32_16x16x32_bf16 v[50:53], v[176:179], v[184:187], v[50:53]
	v_mfma_f32_16x16x32_bf16 v[50:53], v[180:183], v[188:191], v[50:53]
	v_mfma_f32_16x16x32_bf16 v[46:49], v[168:171], v[192:195], v[46:49]
	v_mfma_f32_16x16x32_bf16 v[46:49], v[172:175], v[196:199], v[46:49]
	v_mfma_f32_16x16x32_bf16 v[34:37], v[176:179], v[192:195], v[34:37]
	v_mfma_f32_16x16x32_bf16 v[34:37], v[180:183], v[196:199], v[34:37]
	v_mfma_f32_16x16x32_bf16 v[30:33], v[168:171], v[200:203], v[30:33]
	v_mfma_f32_16x16x32_bf16 v[30:33], v[172:175], v[204:207], v[30:33]
	v_mfma_f32_16x16x32_bf16 v[18:21], v[176:179], v[200:203], v[18:21]
	v_mfma_f32_16x16x32_bf16 v[18:21], v[180:183], v[204:207], v[18:21]
	v_mfma_f32_16x16x32_bf16 v[14:17], v[168:171], v[216:219], v[14:17]
	v_mfma_f32_16x16x32_bf16 v[14:17], v[172:175], v[220:223], v[14:17]
	v_mfma_f32_16x16x32_bf16 v[6:9], v[176:179], v[216:219], v[6:9]
	v_mfma_f32_16x16x32_bf16 v[6:9], v[180:183], v[220:223], v[6:9]
	s_barrier
	s_add_i32 s44, 0, 0x18000
	s_add_i32 s45, 0, 0x1c000
	s_add_u32 s16, vcc_lo, 0x80000
	s_addc_u32 s17, vcc_hi, 0
	s_mov_b32 m0, s24
	v_add_u32_e32 v143, s44, v140
	ds_read_b128 v[136:139], v143
	ds_read_b128 v[144:147], v143 offset:1024
	ds_read_b128 v[148:151], v143 offset:2048
	ds_read_b128 v[152:155], v143 offset:3072
	v_add_u32_e32 v143, s45, v140
	ds_read_b128 v[168:171], v143
	ds_read_b128 v[172:175], v143 offset:1024
	ds_read_b128 v[176:179], v143 offset:2048
	ds_read_b128 v[180:183], v143 offset:3072
	ds_read_b128 v[184:187], v142 offset:32768
	ds_read_b128 v[188:191], v142 offset:33792
	ds_read_b128 v[192:195], v142 offset:34816
	ds_read_b128 v[196:199], v142 offset:35840
	ds_read_b128 v[200:203], v142 offset:36864
	ds_read_b128 v[204:207], v142 offset:37888
	ds_read_b128 v[216:219], v142 offset:38912
	ds_read_b128 v[220:223], v142 offset:39936
	global_load_lds_dwordx4 v130, s[16:17]
	s_mov_b32 m0, s25
	s_nop 0
	global_load_lds_dwordx4 v132, s[16:17]
	s_waitcnt vmcnt(8)
	s_waitcnt lgkmcnt(0)
	s_barrier
	s_waitcnt lgkmcnt(0)
	v_mfma_f32_16x16x32_bf16 v[122:125], v[136:139], v[184:187], v[122:125]
	v_mfma_f32_16x16x32_bf16 v[122:125], v[144:147], v[188:191], v[122:125]
	v_mfma_f32_16x16x32_bf16 v[114:117], v[148:151], v[184:187], v[114:117]
	v_mfma_f32_16x16x32_bf16 v[114:117], v[152:155], v[188:191], v[114:117]
	v_mfma_f32_16x16x32_bf16 v[106:109], v[136:139], v[192:195], v[106:109]
	v_mfma_f32_16x16x32_bf16 v[106:109], v[144:147], v[196:199], v[106:109]
	v_mfma_f32_16x16x32_bf16 v[102:105], v[148:151], v[192:195], v[102:105]
	v_mfma_f32_16x16x32_bf16 v[102:105], v[152:155], v[196:199], v[102:105]
	v_mfma_f32_16x16x32_bf16 v[90:93], v[136:139], v[200:203], v[90:93]
	v_mfma_f32_16x16x32_bf16 v[90:93], v[144:147], v[204:207], v[90:93]
	v_mfma_f32_16x16x32_bf16 v[86:89], v[148:151], v[200:203], v[86:89]
	v_mfma_f32_16x16x32_bf16 v[86:89], v[152:155], v[204:207], v[86:89]
	v_mfma_f32_16x16x32_bf16 v[74:77], v[136:139], v[216:219], v[74:77]
	v_mfma_f32_16x16x32_bf16 v[74:77], v[144:147], v[220:223], v[74:77]
	v_mfma_f32_16x16x32_bf16 v[70:73], v[148:151], v[216:219], v[70:73]
	v_mfma_f32_16x16x32_bf16 v[70:73], v[152:155], v[220:223], v[70:73]
	v_mfma_f32_16x16x32_bf16 v[126:129], v[168:171], v[184:187], v[126:129]
	v_mfma_f32_16x16x32_bf16 v[126:129], v[172:175], v[188:191], v[126:129]
	v_mfma_f32_16x16x32_bf16 v[118:121], v[176:179], v[184:187], v[118:121]
	v_mfma_f32_16x16x32_bf16 v[118:121], v[180:183], v[188:191], v[118:121]
	v_mfma_f32_16x16x32_bf16 v[110:113], v[168:171], v[192:195], v[110:113]
	v_mfma_f32_16x16x32_bf16 v[110:113], v[172:175], v[196:199], v[110:113]
	v_mfma_f32_16x16x32_bf16 v[98:101], v[176:179], v[192:195], v[98:101]
	v_mfma_f32_16x16x32_bf16 v[98:101], v[180:183], v[196:199], v[98:101]
	v_mfma_f32_16x16x32_bf16 v[94:97], v[168:171], v[200:203], v[94:97]
	v_mfma_f32_16x16x32_bf16 v[94:97], v[172:175], v[204:207], v[94:97]
	v_mfma_f32_16x16x32_bf16 v[82:85], v[176:179], v[200:203], v[82:85]
	v_mfma_f32_16x16x32_bf16 v[82:85], v[180:183], v[204:207], v[82:85]
	v_mfma_f32_16x16x32_bf16 v[78:81], v[168:171], v[216:219], v[78:81]
	v_mfma_f32_16x16x32_bf16 v[78:81], v[172:175], v[220:223], v[78:81]
	v_mfma_f32_16x16x32_bf16 v[66:69], v[176:179], v[216:219], v[66:69]
	v_mfma_f32_16x16x32_bf16 v[66:69], v[180:183], v[220:223], v[66:69]
	s_barrier
	s_add_i32 s16, s44, s61
	s_mov_b32 m0, s16
	s_add_u32 s14, s14, 0x80
	s_addc_u32 s15, s15, 0
	s_add_u32 vcc_lo, vcc_lo, 0x80
	s_addc_u32 vcc_hi, vcc_hi, 0
	ds_read_b128 v[184:187], v142 offset:49152
	ds_read_b128 v[188:191], v142 offset:50176
	ds_read_b128 v[192:195], v142 offset:51200
	ds_read_b128 v[196:199], v142 offset:52224
	ds_read_b128 v[200:203], v142 offset:53248
	ds_read_b128 v[204:207], v142 offset:54272
	ds_read_b128 v[216:219], v142 offset:55296
	ds_read_b128 v[220:223], v142 offset:56320
	global_load_lds_dwordx4 v158, s[14:15]
	s_add_i32 m0, s16, 0x2000
	s_nop 0
	global_load_lds_dwordx4 v134, s[14:15]
	s_add_u32 s14, s14, 0x80000
	s_addc_u32 s15, s15, 0
	s_add_i32 s16, s45, s61
	s_mov_b32 m0, s16
	s_nop 0
	global_load_lds_dwordx4 v158, s[14:15]
	s_add_i32 m0, s16, 0x2000
	s_nop 0
	global_load_lds_dwordx4 v134, s[14:15]
	s_mov_b32 m0, s26
	s_nop 0
	global_load_lds_dwordx4 v130, vcc
	s_mov_b32 m0, s27
	s_nop 0
	global_load_lds_dwordx4 v132, vcc
	s_waitcnt vmcnt(8)
	s_waitcnt lgkmcnt(0)
	s_barrier
	s_waitcnt lgkmcnt(0)
	v_mfma_f32_16x16x32_bf16 v[58:61], v[136:139], v[184:187], v[58:61]
	v_mfma_f32_16x16x32_bf16 v[58:61], v[144:147], v[188:191], v[58:61]
	v_mfma_f32_16x16x32_bf16 v[54:57], v[148:151], v[184:187], v[54:57]
	v_mfma_f32_16x16x32_bf16 v[54:57], v[152:155], v[188:191], v[54:57]
	v_mfma_f32_16x16x32_bf16 v[42:45], v[136:139], v[192:195], v[42:45]
	v_mfma_f32_16x16x32_bf16 v[42:45], v[144:147], v[196:199], v[42:45]
	v_mfma_f32_16x16x32_bf16 v[38:41], v[148:151], v[192:195], v[38:41]
	v_mfma_f32_16x16x32_bf16 v[38:41], v[152:155], v[196:199], v[38:41]
	v_mfma_f32_16x16x32_bf16 v[26:29], v[136:139], v[200:203], v[26:29]
	v_mfma_f32_16x16x32_bf16 v[26:29], v[144:147], v[204:207], v[26:29]
	v_mfma_f32_16x16x32_bf16 v[22:25], v[148:151], v[200:203], v[22:25]
	v_mfma_f32_16x16x32_bf16 v[22:25], v[152:155], v[204:207], v[22:25]
	v_mfma_f32_16x16x32_bf16 v[10:13], v[136:139], v[216:219], v[10:13]
	v_mfma_f32_16x16x32_bf16 v[10:13], v[144:147], v[220:223], v[10:13]
	v_mfma_f32_16x16x32_bf16 v[2:5], v[148:151], v[216:219], v[2:5]
	v_mfma_f32_16x16x32_bf16 v[2:5], v[152:155], v[220:223], v[2:5]
	v_mfma_f32_16x16x32_bf16 v[62:65], v[168:171], v[184:187], v[62:65]
	v_mfma_f32_16x16x32_bf16 v[62:65], v[172:175], v[188:191], v[62:65]
	v_mfma_f32_16x16x32_bf16 v[50:53], v[176:179], v[184:187], v[50:53]
	v_mfma_f32_16x16x32_bf16 v[50:53], v[180:183], v[188:191], v[50:53]
	v_mfma_f32_16x16x32_bf16 v[46:49], v[168:171], v[192:195], v[46:49]
	v_mfma_f32_16x16x32_bf16 v[46:49], v[172:175], v[196:199], v[46:49]
	v_mfma_f32_16x16x32_bf16 v[34:37], v[176:179], v[192:195], v[34:37]
	v_mfma_f32_16x16x32_bf16 v[34:37], v[180:183], v[196:199], v[34:37]
	v_mfma_f32_16x16x32_bf16 v[30:33], v[168:171], v[200:203], v[30:33]
	v_mfma_f32_16x16x32_bf16 v[30:33], v[172:175], v[204:207], v[30:33]
	v_mfma_f32_16x16x32_bf16 v[18:21], v[176:179], v[200:203], v[18:21]
	v_mfma_f32_16x16x32_bf16 v[18:21], v[180:183], v[204:207], v[18:21]
	v_mfma_f32_16x16x32_bf16 v[14:17], v[168:171], v[216:219], v[14:17]
	v_mfma_f32_16x16x32_bf16 v[14:17], v[172:175], v[220:223], v[14:17]
	v_mfma_f32_16x16x32_bf16 v[6:9], v[176:179], v[216:219], v[6:9]
	v_mfma_f32_16x16x32_bf16 v[6:9], v[180:183], v[220:223], v[6:9]
	s_barrier
	s_cmp_gt_u32 s35, 29
	s_mov_b32 s35, s54
	s_cbranch_scc1 .LBB0_279
